# gla_chunk step-0 staging de-serialized (v-tile and a_low loads issued together, one wait) in phase 3 and phase 1 prompt chunks; plus barrier and conv edits
# speedup vs baseline: 1.0046x; 1.0046x over previous
.LBB0_426:
	v_mov_b32_e32 v73, v0
	s_or_b64 s[0:1], s[0:1], s[94:95]
	v_ashrrev_i32_e32 v77, 7, v73
	v_lshlrev_b32_e32 v72, 4, v77
	v_cmp_gt_i32_e64 s[40:41], 4, v77
	v_and_b32_e32 v76, 0x7f, v73
	v_lshlrev_b32_e32 v172, 1, v76
	v_cndmask_b32_e64 v66, 0, v72, s[40:41]
	v_ashrrev_i32_e32 v67, 31, v66
	v_lshl_add_u64 v[68:69], s[0:1], 0, v[66:67]
	v_mov_b64_e32 v[66:67], s[92:93]
	v_mad_u64_u32 v[70:71], s[20:21], v68, s16, v[66:67]
	v_mov_b32_e32 v68, v71
	v_mad_u64_u32 v[68:69], s[20:21], v69, s16, v[68:69]
	v_mov_b32_e32 v71, v68
	v_lshl_add_u64 v[68:69], v[70:71], 0, s[90:91]
	v_lshl_add_u64 v[68:69], v[68:69], 0, v[172:173]
	v_add_co_u32_e32 v68, vcc, s17, v68
	v_or_b32_e32 v133, 1, v72
	s_nop 0
	v_addc_co_u32_e32 v69, vcc, 0, v69, vcc
	v_cmp_gt_i32_e64 s[42:43], 64, v133
	global_load_ushort v78, v[68:69], off offset:1024
	v_or_b32_e32 v132, 2, v72
	v_cndmask_b32_e64 v68, 0, v133, s[42:43]
	v_ashrrev_i32_e32 v69, 31, v68
	v_lshl_add_u64 v[68:69], s[0:1], 0, v[68:69]
	v_mad_u64_u32 v[70:71], s[20:21], v68, s16, v[66:67]
	v_mov_b32_e32 v68, v71
	v_mad_u64_u32 v[68:69], s[20:21], v69, s16, v[68:69]
	v_mov_b32_e32 v71, v68
	v_lshl_add_u64 v[68:69], v[70:71], 0, s[90:91]
	v_lshl_add_u64 v[68:69], v[68:69], 0, v[172:173]
	v_add_co_u32_e32 v68, vcc, s17, v68
	v_cmp_gt_i32_e64 s[44:45], 64, v132
	s_nop 0
	v_addc_co_u32_e32 v69, vcc, 0, v69, vcc
	global_load_ushort v79, v[68:69], off offset:1024
	v_cndmask_b32_e64 v68, 0, v132, s[44:45]
	v_ashrrev_i32_e32 v69, 31, v68
	v_lshl_add_u64 v[68:69], s[0:1], 0, v[68:69]
	v_mad_u64_u32 v[70:71], s[20:21], v68, s16, v[66:67]
	v_mov_b32_e32 v68, v71
	v_mad_u64_u32 v[68:69], s[20:21], v69, s16, v[68:69]
	v_mov_b32_e32 v71, v68
	v_lshl_add_u64 v[68:69], v[70:71], 0, s[90:91]
	v_lshl_add_u64 v[68:69], v[68:69], 0, v[172:173]
	v_add_co_u32_e32 v68, vcc, s17, v68
	v_or_b32_e32 v131, 3, v72
	s_nop 0
	v_addc_co_u32_e32 v69, vcc, 0, v69, vcc
	v_cmp_gt_i32_e64 s[46:47], 64, v131
	global_load_ushort v80, v[68:69], off offset:1024
	v_or_b32_e32 v130, 4, v72
	v_cndmask_b32_e64 v68, 0, v131, s[46:47]
	v_ashrrev_i32_e32 v69, 31, v68
	v_lshl_add_u64 v[68:69], s[0:1], 0, v[68:69]
	v_mad_u64_u32 v[70:71], s[20:21], v68, s16, v[66:67]
	v_mov_b32_e32 v68, v71
	v_mad_u64_u32 v[68:69], s[20:21], v69, s16, v[68:69]
	v_mov_b32_e32 v71, v68
	v_lshl_add_u64 v[68:69], v[70:71], 0, s[90:91]
	v_lshl_add_u64 v[68:69], v[68:69], 0, v[172:173]
	v_add_co_u32_e32 v68, vcc, s17, v68
	v_cmp_gt_i32_e64 s[48:49], 64, v130
	s_nop 0
	v_addc_co_u32_e32 v69, vcc, 0, v69, vcc
	global_load_ushort v81, v[68:69], off offset:1024
	v_cndmask_b32_e64 v68, 0, v130, s[48:49]
	v_ashrrev_i32_e32 v69, 31, v68
	v_lshl_add_u64 v[68:69], s[0:1], 0, v[68:69]
	v_mad_u64_u32 v[70:71], s[20:21], v68, s16, v[66:67]
	v_mov_b32_e32 v68, v71
	v_mad_u64_u32 v[68:69], s[20:21], v69, s16, v[68:69]
	v_mov_b32_e32 v71, v68
	v_lshl_add_u64 v[68:69], v[70:71], 0, s[90:91]
	v_lshl_add_u64 v[68:69], v[68:69], 0, v[172:173]
	v_add_co_u32_e32 v68, vcc, s17, v68
	v_or_b32_e32 v129, 5, v72
	s_nop 0
	v_addc_co_u32_e32 v69, vcc, 0, v69, vcc
	v_cmp_gt_i32_e64 s[50:51], 64, v129
	global_load_ushort v106, v[68:69], off offset:1024
	v_or_b32_e32 v128, 6, v72
	v_cndmask_b32_e64 v68, 0, v129, s[50:51]
	v_ashrrev_i32_e32 v69, 31, v68
	v_lshl_add_u64 v[68:69], s[0:1], 0, v[68:69]
	v_mad_u64_u32 v[70:71], s[20:21], v68, s16, v[66:67]
	v_mov_b32_e32 v68, v71
	v_mad_u64_u32 v[68:69], s[20:21], v69, s16, v[68:69]
	v_mov_b32_e32 v71, v68
	v_lshl_add_u64 v[68:69], v[70:71], 0, s[90:91]
	v_lshl_add_u64 v[68:69], v[68:69], 0, v[172:173]
	v_add_co_u32_e32 v68, vcc, s17, v68
	v_cmp_gt_i32_e64 s[52:53], 64, v128
	s_nop 0
	v_addc_co_u32_e32 v69, vcc, 0, v69, vcc
	global_load_ushort v107, v[68:69], off offset:1024
	v_cndmask_b32_e64 v68, 0, v128, s[52:53]
	v_ashrrev_i32_e32 v69, 31, v68
	v_lshl_add_u64 v[68:69], s[0:1], 0, v[68:69]
	v_mad_u64_u32 v[70:71], s[20:21], v68, s16, v[66:67]
	v_mov_b32_e32 v68, v71
	v_mad_u64_u32 v[68:69], s[20:21], v69, s16, v[68:69]
	v_mov_b32_e32 v71, v68
	v_lshl_add_u64 v[68:69], v[70:71], 0, s[90:91]
	v_lshl_add_u64 v[68:69], v[68:69], 0, v[172:173]
	v_add_co_u32_e32 v68, vcc, s17, v68
	v_or_b32_e32 v127, 7, v72
	s_nop 0
	v_addc_co_u32_e32 v69, vcc, 0, v69, vcc
	v_cmp_gt_i32_e64 s[54:55], 64, v127
	global_load_ushort v108, v[68:69], off offset:1024
	v_or_b32_e32 v126, 8, v72
	v_cndmask_b32_e64 v68, 0, v127, s[54:55]
	v_ashrrev_i32_e32 v69, 31, v68
	v_lshl_add_u64 v[68:69], s[0:1], 0, v[68:69]
	v_mad_u64_u32 v[70:71], s[20:21], v68, s16, v[66:67]
	v_mov_b32_e32 v68, v71
	v_mad_u64_u32 v[68:69], s[20:21], v69, s16, v[68:69]
	v_mov_b32_e32 v71, v68
	v_lshl_add_u64 v[68:69], v[70:71], 0, s[90:91]
	v_lshl_add_u64 v[68:69], v[68:69], 0, v[172:173]
	v_add_co_u32_e32 v68, vcc, s17, v68
	v_cmp_gt_i32_e64 s[56:57], 64, v126
	s_nop 0
	v_addc_co_u32_e32 v69, vcc, 0, v69, vcc
	global_load_ushort v109, v[68:69], off offset:1024
	v_cndmask_b32_e64 v68, 0, v126, s[56:57]
	v_ashrrev_i32_e32 v69, 31, v68
	v_lshl_add_u64 v[68:69], s[0:1], 0, v[68:69]
	v_mad_u64_u32 v[70:71], s[20:21], v68, s16, v[66:67]
	v_mov_b32_e32 v68, v71
	v_mad_u64_u32 v[68:69], s[20:21], v69, s16, v[68:69]
	v_mov_b32_e32 v71, v68
	v_lshl_add_u64 v[68:69], v[70:71], 0, s[90:91]
	v_lshl_add_u64 v[68:69], v[68:69], 0, v[172:173]
	v_add_co_u32_e32 v68, vcc, s17, v68
	v_or_b32_e32 v125, 9, v72
	s_nop 0
	v_addc_co_u32_e32 v69, vcc, 0, v69, vcc
	v_cmp_gt_i32_e64 s[58:59], 64, v125
	global_load_ushort v110, v[68:69], off offset:1024
	v_or_b32_e32 v124, 10, v72
	v_cndmask_b32_e64 v68, 0, v125, s[58:59]
	v_ashrrev_i32_e32 v69, 31, v68
	v_lshl_add_u64 v[68:69], s[0:1], 0, v[68:69]
	v_mad_u64_u32 v[70:71], s[20:21], v68, s16, v[66:67]
	v_mov_b32_e32 v68, v71
	v_mad_u64_u32 v[68:69], s[20:21], v69, s16, v[68:69]
	v_mov_b32_e32 v71, v68
	v_lshl_add_u64 v[68:69], v[70:71], 0, s[90:91]
	v_lshl_add_u64 v[68:69], v[68:69], 0, v[172:173]
	v_add_co_u32_e32 v68, vcc, s17, v68
	v_cmp_gt_i32_e64 s[60:61], 64, v124
	s_nop 0
	v_addc_co_u32_e32 v69, vcc, 0, v69, vcc
	global_load_ushort v111, v[68:69], off offset:1024
	v_cndmask_b32_e64 v68, 0, v124, s[60:61]
	v_ashrrev_i32_e32 v69, 31, v68
	v_lshl_add_u64 v[68:69], s[0:1], 0, v[68:69]
	v_mad_u64_u32 v[70:71], s[20:21], v68, s16, v[66:67]
	v_mov_b32_e32 v68, v71
	v_mad_u64_u32 v[68:69], s[20:21], v69, s16, v[68:69]
	v_mov_b32_e32 v71, v68
	v_lshl_add_u64 v[68:69], v[70:71], 0, s[90:91]
	v_lshl_add_u64 v[68:69], v[68:69], 0, v[172:173]
	v_add_co_u32_e32 v68, vcc, s17, v68
	v_or_b32_e32 v123, 11, v72
	s_nop 0
	v_addc_co_u32_e32 v69, vcc, 0, v69, vcc
	v_cmp_gt_i32_e64 s[62:63], 64, v123
	global_load_ushort v112, v[68:69], off offset:1024
	v_or_b32_e32 v122, 12, v72
	v_cndmask_b32_e64 v68, 0, v123, s[62:63]
	v_ashrrev_i32_e32 v69, 31, v68
	v_lshl_add_u64 v[68:69], s[0:1], 0, v[68:69]
	v_mad_u64_u32 v[70:71], s[20:21], v68, s16, v[66:67]
	v_mov_b32_e32 v68, v71
	v_mad_u64_u32 v[68:69], s[20:21], v69, s16, v[68:69]
	v_mov_b32_e32 v71, v68
	v_lshl_add_u64 v[68:69], v[70:71], 0, s[90:91]
	v_lshl_add_u64 v[68:69], v[68:69], 0, v[172:173]
	v_add_co_u32_e32 v68, vcc, s17, v68
	v_cmp_gt_i32_e64 s[64:65], 64, v122
	s_nop 0
	v_addc_co_u32_e32 v69, vcc, 0, v69, vcc
	global_load_ushort v113, v[68:69], off offset:1024
	v_cndmask_b32_e64 v68, 0, v122, s[64:65]
	v_ashrrev_i32_e32 v69, 31, v68
	v_lshl_add_u64 v[68:69], s[0:1], 0, v[68:69]
	v_mad_u64_u32 v[70:71], s[20:21], v68, s16, v[66:67]
	v_mov_b32_e32 v68, v71
	v_mad_u64_u32 v[68:69], s[20:21], v69, s16, v[68:69]
	v_mov_b32_e32 v71, v68
	v_lshl_add_u64 v[68:69], v[70:71], 0, s[90:91]
	v_lshl_add_u64 v[68:69], v[68:69], 0, v[172:173]
	v_add_co_u32_e32 v68, vcc, s17, v68
	v_or_b32_e32 v121, 13, v72
	s_nop 0
	v_addc_co_u32_e32 v69, vcc, 0, v69, vcc
	v_cmp_gt_i32_e64 s[66:67], 64, v121
	global_load_ushort v114, v[68:69], off offset:1024
	v_or_b32_e32 v120, 14, v72
	v_cndmask_b32_e64 v68, 0, v121, s[66:67]
	v_ashrrev_i32_e32 v69, 31, v68
	v_lshl_add_u64 v[68:69], s[0:1], 0, v[68:69]
	v_mad_u64_u32 v[70:71], s[20:21], v68, s16, v[66:67]
	v_mov_b32_e32 v68, v71
	v_mad_u64_u32 v[68:69], s[20:21], v69, s16, v[68:69]
	v_mov_b32_e32 v71, v68
	v_lshl_add_u64 v[68:69], v[70:71], 0, s[90:91]
	v_lshl_add_u64 v[68:69], v[68:69], 0, v[172:173]
	v_add_co_u32_e32 v68, vcc, s17, v68
	v_cmp_gt_i32_e64 s[68:69], 64, v120
	s_nop 0
	v_addc_co_u32_e32 v69, vcc, 0, v69, vcc
	global_load_ushort v115, v[68:69], off offset:1024
	v_cndmask_b32_e64 v68, 0, v120, s[68:69]
	v_ashrrev_i32_e32 v69, 31, v68
	v_lshl_add_u64 v[68:69], s[0:1], 0, v[68:69]
	v_mad_u64_u32 v[70:71], s[20:21], v68, s16, v[66:67]
	v_mov_b32_e32 v68, v71
	v_mad_u64_u32 v[68:69], s[20:21], v69, s16, v[68:69]
	v_mov_b32_e32 v71, v68
	v_lshl_add_u64 v[68:69], v[70:71], 0, s[90:91]
	v_lshl_add_u64 v[68:69], v[68:69], 0, v[172:173]
	v_add_co_u32_e32 v68, vcc, s17, v68
	v_or_b32_e32 v119, 15, v72
	s_nop 0
	v_addc_co_u32_e32 v69, vcc, 0, v69, vcc
	v_cmp_gt_i32_e64 s[70:71], 64, v119
	global_load_ushort v116, v[68:69], off offset:1024
	s_nop 0
	v_cndmask_b32_e64 v68, 0, v119, s[70:71]
	v_ashrrev_i32_e32 v69, 31, v68
	v_lshl_add_u64 v[68:69], s[0:1], 0, v[68:69]
	v_mad_u64_u32 v[66:67], s[20:21], v68, s16, v[66:67]
	v_mov_b32_e32 v68, v67
	v_mad_u64_u32 v[68:69], s[20:21], v69, s16, v[68:69]
	v_mov_b32_e32 v67, v68
	v_lshl_add_u64 v[66:67], v[66:67], 0, s[90:91]
	v_lshl_add_u64 v[66:67], v[66:67], 0, v[172:173]
	v_add_co_u32_e32 v66, vcc, 0x1000, v66
	s_nop 1
	v_addc_co_u32_e32 v67, vcc, 0, v67, vcc
	global_load_ushort v117, v[66:67], off offset:1024
	v_ashrrev_i32_e32 v206, 5, v73
	v_and_b32_e32 v205, 31, v73
	v_ashrrev_i32_e32 v207, 31, v206
	v_lshl_add_u64 v[224:225], s[0:1], 0, v[206:207]
	v_mov_b64_e32 v[226:227], s[92:93]
	v_mad_u64_u32 v[226:227], vcc, v224, s16, v[226:227]
	v_mov_b32_e32 v224, v227
	v_mad_u64_u32 v[224:225], vcc, v225, s16, v[224:225]
	v_mov_b32_e32 v227, v224
	s_lshl_b32 vcc_lo, s83, 1
	s_mov_b32 vcc_hi, s91
	v_lshl_add_u64 v[224:225], v[226:227], 0, vcc
	v_lshlrev_b32_e32 v226, 4, v205
	v_mov_b32_e32 v227, v173
	v_lshl_add_u64 v[224:225], v[224:225], 0, v[226:227]
	v_add_co_u32_e32 v224, vcc, 0x1000, v224
	s_nop 1
	v_addc_co_u32_e32 v225, vcc, 0, v225, vcc
	global_load_dwordx4 v[208:211], v[224:225], off offset:2048
	v_add_co_u32_e32 v224, vcc, 0x70000, v224
	s_nop 1
	v_addc_co_u32_e32 v225, vcc, 0, v225, vcc
	global_load_dwordx4 v[212:215], v[224:225], off offset:2048
	v_add_co_u32_e32 v224, vcc, 0x70000, v224
	s_nop 1
	v_addc_co_u32_e32 v225, vcc, 0, v225, vcc
	global_load_dwordx4 v[216:219], v[224:225], off offset:2048
	v_add_co_u32_e32 v224, vcc, 0x70000, v224
	s_nop 1
	v_addc_co_u32_e32 v225, vcc, 0, v225, vcc
	global_load_dwordx4 v[220:223], v[224:225], off offset:2048
	v_mul_u32_u24_e32 v204, 0x210, v206
	v_lshl_add_u32 v204, v205, 4, v204
	v_add_u32_e32 v204, 0xf400, v204
	v_cmp_gt_i32_e32 vcc, s4, v73
	s_and_saveexec_b64 s[20:21], vcc
	s_cbranch_execz .LBB0_428
	v_ashrrev_i32_e32 v70, 2, v73
	v_ashrrev_i32_e32 v71, 31, v70
	v_lshl_add_u64 v[66:67], s[0:1], 0, v[70:71]
	v_lshlrev_b64 v[66:67], 6, v[66:67]
	v_lshlrev_b32_e32 v68, 4, v73
	v_lshl_add_u64 v[66:67], s[36:37], 0, v[66:67]
	v_and_b32_e32 v172, 48, v68
	v_lshl_add_u64 v[74:75], v[66:67], 0, v[172:173]
	v_add_co_u32_e32 v134, vcc, 0x90000, v74
	global_load_dwordx4 v[66:69], v[74:75], off
	s_nop 0
	v_addc_co_u32_e32 v135, vcc, 0, v75, vcc
	global_load_dwordx4 v[134:137], v[134:135], off
	v_lshlrev_b32_e32 v70, 6, v70
	v_add3_u32 v70, s13, v70, v172
	v_add_co_u32_e32 v228, vcc, 0x120000, v74
	s_nop 1
	v_addc_co_u32_e32 v229, vcc, 0, v75, vcc
	global_load_dwordx4 v[230:233], v[228:229], off
	v_add_co_u32_e32 v228, vcc, 0x1b0000, v74
	s_nop 1
	v_addc_co_u32_e32 v229, vcc, 0, v75, vcc
	global_load_dwordx4 v[234:237], v[228:229], off
	s_waitcnt vmcnt(0)
	v_pk_add_f32 v[142:143], v[66:67], v[134:135]
	v_pk_add_f32 v[138:139], v[68:69], v[136:137]
	v_pk_add_f32 v[68:69], v[232:233], v[236:237]
	v_pk_add_f32 v[66:67], v[230:231], v[234:235]
	v_pk_add_f32 v[68:69], v[138:139], v[68:69]
	v_pk_add_f32 v[66:67], v[142:143], v[66:67]
	ds_write_b128 v70, v[66:69]
.LBB0_428:
	s_or_b64 exec, exec, s[20:21]
	v_and_b32_e32 v118, 31, v73
	s_waitcnt vmcnt(0)
	ds_write_b128 v204, v[208:211]
	ds_write_b128 v204, v[212:215] offset:8448
	ds_write_b128 v204, v[216:219] offset:16896
	ds_write_b128 v204, v[220:223] offset:25344
	v_mov_b32_e32 v66, 0
	v_mov_b32_e32 v70, 0
	s_waitcnt lgkmcnt(0)
	s_barrier
	s_and_saveexec_b64 s[20:21], s[40:41]
	s_cbranch_execz .LBB0_438
	v_lshl_add_u32 v67, v77, 10, 0
	v_add_u32_e32 v67, 0x17800, v67
	ds_read_b128 v[68:71], v67
	ds_read_b128 v[134:137], v67 offset:16
	ds_read_b128 v[142:145], v67 offset:32
	ds_read_b128 v[146:149], v67 offset:48
	s_waitcnt lgkmcnt(3)
	v_mov_b32_e32 v74, v68
	s_waitcnt lgkmcnt(2)
	v_mov_b32_e32 v75, v134
	v_mov_b32_e32 v134, v69
	v_pk_mul_f32 v[68:69], v[86:87], v[134:135]
	s_nop 0
	v_pk_fma_f32 v[68:69], v[84:85], v[74:75], v[68:69]
	v_mov_b32_e32 v74, v70
	v_mov_b32_e32 v75, v136
	v_pk_fma_f32 v[68:69], v[88:89], v[74:75], v[68:69]
	v_mov_b32_e32 v136, v71
	v_pk_fma_f32 v[68:69], v[90:91], v[136:137], v[68:69]
	s_nop 0
	v_add_f32_e32 v67, v105, v68
	v_add_f32_e32 v67, v67, v69
	s_waitcnt lgkmcnt(0)
	v_mov_b32_e32 v69, v146
	v_mov_b32_e32 v146, v143
	v_mov_b32_e32 v68, v142
	v_pk_mul_f32 v[70:71], v[94:95], v[146:147]
	s_nop 0
	v_pk_fma_f32 v[68:69], v[92:93], v[68:69], v[70:71]
	v_mov_b32_e32 v70, v144
	v_mov_b32_e32 v71, v148
	v_pk_fma_f32 v[68:69], v[96:97], v[70:71], v[68:69]
	v_mov_b32_e32 v148, v145
	v_pk_fma_f32 v[68:69], v[102:103], v[148:149], v[68:69]
	s_nop 0
	v_add_f32_e32 v67, v67, v68
	v_add_f32_e32 v67, v67, v69
	v_mul_f32_e64 v68, |v67|, s75
	v_exp_f32_e32 v68, v68
	v_min_f32_e32 v67, 0, v67
	v_add_f32_e32 v68, 1.0, v68
	v_cmp_gt_f32_e32 vcc, s25, v68
	s_nop 1
	v_cndmask_b32_e64 v69, 0, 32, vcc
	v_ldexp_f32 v68, v68, v69
	v_log_f32_e32 v68, v68
	s_nop 0
	v_mul_f32_e32 v69, 0x3f317217, v68
	v_fma_f32 v69, v68, s72, -v69
	v_fmac_f32_e32 v69, 0x3377d1cf, v68
	v_fmac_f32_e32 v69, 0x3f317217, v68
	v_cmp_lt_f32_e64 s[0:1], |v68|, s74
	s_nop 1
	v_cndmask_b32_e64 v68, v68, v69, s[0:1]
	v_cndmask_b32_e32 v69, 0, v202, vcc
	v_sub_f32_e32 v68, v68, v69
	v_sub_f32_e32 v67, v67, v68
	v_fma_f32 v70, v67, s73, 0

.LBB0_781:
	v_mov_b32_e32 v83, v0
	s_or_b64 s[88:89], s[0:1], s[28:29]
	v_ashrrev_i32_e32 v76, 7, v83
	v_lshlrev_b32_e32 v77, 4, v76
	v_cmp_gt_i32_e64 s[70:71], 4, v76
	v_or_b32_e32 v90, 1, v77
	v_cmp_gt_i32_e64 s[68:69], 64, v90
	v_cndmask_b32_e64 v66, 0, v77, s[70:71]
	v_ashrrev_i32_e32 v67, 31, v66
	v_lshl_add_u64 v[68:69], s[88:89], 0, v[66:67]
	v_mov_b64_e32 v[66:67], s[92:93]
	v_mad_u64_u32 v[70:71], s[0:1], v68, s16, v[66:67]
	v_mov_b32_e32 v68, v71
	v_mad_u64_u32 v[68:69], s[0:1], v69, s16, v[68:69]
	v_mov_b32_e32 v71, v68
	v_lshl_add_u64 v[68:69], v[70:71], 0, s[90:91]
	v_cndmask_b32_e64 v70, 0, v90, s[68:69]
	v_ashrrev_i32_e32 v71, 31, v70
	v_lshl_add_u64 v[70:71], s[88:89], 0, v[70:71]
	v_mad_u64_u32 v[74:75], s[0:1], v70, s16, v[66:67]
	v_mov_b32_e32 v70, v75
	v_mad_u64_u32 v[70:71], s[0:1], v71, s16, v[70:71]
	v_or_b32_e32 v165, 2, v77
	v_mov_b32_e32 v75, v70
	v_cmp_gt_i32_e64 s[66:67], 64, v165
	v_lshl_add_u64 v[70:71], v[74:75], 0, s[90:91]
	v_and_b32_e32 v73, 0x7f, v83
	v_cndmask_b32_e64 v74, 0, v165, s[66:67]
	v_ashrrev_i32_e32 v75, 31, v74
	v_lshl_add_u64 v[74:75], s[88:89], 0, v[74:75]
	v_mad_u64_u32 v[78:79], s[0:1], v74, s16, v[66:67]
	v_mov_b32_e32 v72, v79
	v_mad_u64_u32 v[74:75], s[0:1], v75, s16, v[72:73]
	v_or_b32_e32 v164, 3, v77
	v_mov_b32_e32 v79, v74
	v_cmp_gt_i32_e64 s[64:65], 64, v164
	v_lshl_add_u64 v[74:75], v[78:79], 0, s[90:91]
	v_lshlrev_b32_e32 v172, 1, v73
	v_cndmask_b32_e64 v78, 0, v164, s[64:65]
	v_ashrrev_i32_e32 v79, 31, v78
	v_lshl_add_u64 v[68:69], v[68:69], 0, v[172:173]
	v_lshl_add_u64 v[78:79], s[88:89], 0, v[78:79]
	v_add_co_u32_e32 v68, vcc, s17, v68
	v_mad_u64_u32 v[80:81], s[0:1], v78, s16, v[66:67]
	s_nop 0
	v_addc_co_u32_e32 v69, vcc, 0, v69, vcc
	v_lshl_add_u64 v[70:71], v[70:71], 0, v[172:173]
	v_mov_b32_e32 v72, v81
	v_add_co_u32_e32 v70, vcc, s17, v70
	v_mad_u64_u32 v[78:79], s[0:1], v79, s16, v[72:73]
	s_nop 0
	v_addc_co_u32_e32 v71, vcc, 0, v71, vcc
	v_lshl_add_u64 v[74:75], v[74:75], 0, v[172:173]
	v_mov_b32_e32 v81, v78
	v_add_co_u32_e32 v74, vcc, s17, v74
	v_lshl_add_u64 v[78:79], v[80:81], 0, s[90:91]
	s_nop 0
	v_addc_co_u32_e32 v75, vcc, 0, v75, vcc
	v_lshl_add_u64 v[78:79], v[78:79], 0, v[172:173]
	v_or_b32_e32 v163, 4, v77
	v_add_co_u32_e32 v78, vcc, s17, v78
	v_cmp_gt_i32_e64 s[62:63], 64, v163
	s_nop 0
	v_addc_co_u32_e32 v79, vcc, 0, v79, vcc
	global_load_ushort v129, v[68:69], off
	global_load_ushort v130, v[68:69], off offset:1024
	global_load_ushort v127, v[70:71], off
	global_load_ushort v128, v[70:71], off offset:1024
	global_load_ushort v123, v[74:75], off
	global_load_ushort v124, v[74:75], off offset:1024
	global_load_ushort v97, v[78:79], off
	global_load_ushort v118, v[78:79], off offset:1024
	v_cndmask_b32_e64 v68, 0, v163, s[62:63]
	v_ashrrev_i32_e32 v69, 31, v68
	v_lshl_add_u64 v[68:69], s[88:89], 0, v[68:69]
	v_mad_u64_u32 v[70:71], s[0:1], v68, s16, v[66:67]
	v_mov_b32_e32 v68, v71
	v_mad_u64_u32 v[68:69], s[0:1], v69, s16, v[68:69]
	v_or_b32_e32 v162, 5, v77
	v_mov_b32_e32 v71, v68
	v_cmp_gt_i32_e64 s[60:61], 64, v162
	v_lshl_add_u64 v[68:69], v[70:71], 0, s[90:91]
	v_or_b32_e32 v161, 6, v77
	v_cndmask_b32_e64 v70, 0, v162, s[60:61]
	v_ashrrev_i32_e32 v71, 31, v70
	v_lshl_add_u64 v[70:71], s[88:89], 0, v[70:71]
	v_mad_u64_u32 v[74:75], s[0:1], v70, s16, v[66:67]
	v_mov_b32_e32 v70, v75
	v_mad_u64_u32 v[70:71], s[0:1], v71, s16, v[70:71]
	v_mov_b32_e32 v75, v70
	v_cmp_gt_i32_e64 s[58:59], 64, v161
	v_lshl_add_u64 v[70:71], v[74:75], 0, s[90:91]
	v_or_b32_e32 v160, 7, v77
	v_cndmask_b32_e64 v74, 0, v161, s[58:59]
	v_ashrrev_i32_e32 v75, 31, v74
	v_lshl_add_u64 v[74:75], s[88:89], 0, v[74:75]
	v_mad_u64_u32 v[78:79], s[0:1], v74, s16, v[66:67]
	v_mov_b32_e32 v72, v79
	v_mad_u64_u32 v[74:75], s[0:1], v75, s16, v[72:73]
	v_mov_b32_e32 v79, v74
	v_cmp_gt_i32_e64 s[56:57], 64, v160
	v_lshl_add_u64 v[74:75], v[78:79], 0, s[90:91]
	v_lshl_add_u64 v[68:69], v[68:69], 0, v[172:173]
	v_cndmask_b32_e64 v78, 0, v160, s[56:57]
	v_ashrrev_i32_e32 v79, 31, v78
	v_lshl_add_u64 v[78:79], s[88:89], 0, v[78:79]
	v_add_co_u32_e32 v68, vcc, s17, v68
	v_mad_u64_u32 v[80:81], s[0:1], v78, s16, v[66:67]
	s_nop 0
	v_addc_co_u32_e32 v69, vcc, 0, v69, vcc
	v_lshl_add_u64 v[70:71], v[70:71], 0, v[172:173]
	v_mov_b32_e32 v72, v81
	v_add_co_u32_e32 v70, vcc, s17, v70
	v_mad_u64_u32 v[78:79], s[0:1], v79, s16, v[72:73]
	s_nop 0
	v_addc_co_u32_e32 v71, vcc, 0, v71, vcc
	v_lshl_add_u64 v[74:75], v[74:75], 0, v[172:173]
	v_mov_b32_e32 v81, v78
	v_add_co_u32_e32 v74, vcc, s17, v74
	v_lshl_add_u64 v[78:79], v[80:81], 0, s[90:91]
	s_nop 0
	v_addc_co_u32_e32 v75, vcc, 0, v75, vcc
	v_lshl_add_u64 v[78:79], v[78:79], 0, v[172:173]
	v_or_b32_e32 v159, 8, v77
	v_add_co_u32_e32 v78, vcc, s17, v78
	v_cmp_gt_i32_e64 s[54:55], 64, v159
	s_nop 0
	v_addc_co_u32_e32 v79, vcc, 0, v79, vcc
	global_load_ushort v125, v[68:69], off
	global_load_ushort v126, v[68:69], off offset:1024
	global_load_ushort v121, v[70:71], off
	global_load_ushort v122, v[70:71], off offset:1024
	global_load_ushort v95, v[74:75], off
	global_load_ushort v96, v[74:75], off offset:1024
	global_load_ushort v88, v[78:79], off
	global_load_ushort v89, v[78:79], off offset:1024
	v_cndmask_b32_e64 v68, 0, v159, s[54:55]
	v_ashrrev_i32_e32 v69, 31, v68
	v_lshl_add_u64 v[68:69], s[88:89], 0, v[68:69]
	v_mad_u64_u32 v[70:71], s[0:1], v68, s16, v[66:67]
	v_mov_b32_e32 v68, v71
	v_mad_u64_u32 v[68:69], s[0:1], v69, s16, v[68:69]
	v_or_b32_e32 v158, 9, v77
	v_mov_b32_e32 v71, v68
	v_cmp_gt_i32_e64 s[52:53], 64, v158
	v_lshl_add_u64 v[68:69], v[70:71], 0, s[90:91]
	v_or_b32_e32 v157, 10, v77
	v_cndmask_b32_e64 v70, 0, v158, s[52:53]
	v_ashrrev_i32_e32 v71, 31, v70
	v_lshl_add_u64 v[70:71], s[88:89], 0, v[70:71]
	v_mad_u64_u32 v[74:75], s[0:1], v70, s16, v[66:67]
	v_mov_b32_e32 v70, v75
	v_mad_u64_u32 v[70:71], s[0:1], v71, s16, v[70:71]
	v_mov_b32_e32 v75, v70
	v_cmp_gt_i32_e64 s[50:51], 64, v157
	v_lshl_add_u64 v[70:71], v[74:75], 0, s[90:91]
	v_or_b32_e32 v156, 11, v77
	v_cndmask_b32_e64 v74, 0, v157, s[50:51]
	v_ashrrev_i32_e32 v75, 31, v74
	v_lshl_add_u64 v[74:75], s[88:89], 0, v[74:75]
	v_mad_u64_u32 v[78:79], s[0:1], v74, s16, v[66:67]
	v_mov_b32_e32 v72, v79
	v_mad_u64_u32 v[74:75], s[0:1], v75, s16, v[72:73]
	v_mov_b32_e32 v79, v74
	v_cmp_gt_i32_e64 s[48:49], 64, v156
	v_lshl_add_u64 v[74:75], v[78:79], 0, s[90:91]
	v_lshl_add_u64 v[68:69], v[68:69], 0, v[172:173]
	v_cndmask_b32_e64 v78, 0, v156, s[48:49]
	v_ashrrev_i32_e32 v79, 31, v78
	v_lshl_add_u64 v[78:79], s[88:89], 0, v[78:79]
	v_add_co_u32_e32 v68, vcc, s17, v68
	v_mad_u64_u32 v[80:81], s[0:1], v78, s16, v[66:67]
	s_nop 0
	v_addc_co_u32_e32 v69, vcc, 0, v69, vcc
	v_lshl_add_u64 v[70:71], v[70:71], 0, v[172:173]
	v_mov_b32_e32 v72, v81
	v_add_co_u32_e32 v70, vcc, s17, v70
	v_mad_u64_u32 v[78:79], s[0:1], v79, s16, v[72:73]
	s_nop 0
	v_addc_co_u32_e32 v71, vcc, 0, v71, vcc
	v_lshl_add_u64 v[74:75], v[74:75], 0, v[172:173]
	v_mov_b32_e32 v81, v78
	v_add_co_u32_e32 v74, vcc, s17, v74
	v_lshl_add_u64 v[78:79], v[80:81], 0, s[90:91]
	s_nop 0
	v_addc_co_u32_e32 v75, vcc, 0, v75, vcc
	v_lshl_add_u64 v[78:79], v[78:79], 0, v[172:173]
	v_or_b32_e32 v155, 12, v77
	v_add_co_u32_e32 v78, vcc, s17, v78
	v_cmp_gt_i32_e64 s[46:47], 64, v155
	s_nop 0
	v_addc_co_u32_e32 v79, vcc, 0, v79, vcc
	global_load_ushort v119, v[68:69], off
	global_load_ushort v120, v[68:69], off offset:1024
	global_load_ushort v93, v[70:71], off
	global_load_ushort v94, v[70:71], off offset:1024
	global_load_ushort v86, v[74:75], off
	global_load_ushort v87, v[74:75], off offset:1024
	global_load_ushort v81, v[78:79], off
	global_load_ushort v82, v[78:79], off offset:1024
	v_cndmask_b32_e64 v68, 0, v155, s[46:47]
	v_ashrrev_i32_e32 v69, 31, v68
	v_lshl_add_u64 v[68:69], s[88:89], 0, v[68:69]
	v_mad_u64_u32 v[70:71], s[0:1], v68, s16, v[66:67]
	v_mov_b32_e32 v68, v71
	v_mad_u64_u32 v[68:69], s[0:1], v69, s16, v[68:69]
	v_or_b32_e32 v133, 13, v77
	v_mov_b32_e32 v71, v68
	v_cmp_gt_i32_e64 s[44:45], 64, v133
	v_lshl_add_u64 v[68:69], v[70:71], 0, s[90:91]
	v_or_b32_e32 v132, 14, v77
	v_cndmask_b32_e64 v70, 0, v133, s[44:45]
	v_ashrrev_i32_e32 v71, 31, v70
	v_lshl_add_u64 v[70:71], s[88:89], 0, v[70:71]
	v_mad_u64_u32 v[74:75], s[0:1], v70, s16, v[66:67]
	v_mov_b32_e32 v70, v75
	v_mad_u64_u32 v[70:71], s[0:1], v71, s16, v[70:71]
	v_mov_b32_e32 v75, v70
	v_cmp_gt_i32_e64 s[42:43], 64, v132
	v_lshl_add_u64 v[70:71], v[74:75], 0, s[90:91]
	v_or_b32_e32 v131, 15, v77
	v_cndmask_b32_e64 v74, 0, v132, s[42:43]
	v_ashrrev_i32_e32 v75, 31, v74
	v_lshl_add_u64 v[74:75], s[88:89], 0, v[74:75]
	v_mad_u64_u32 v[78:79], s[0:1], v74, s16, v[66:67]
	v_mov_b32_e32 v72, v79
	v_mad_u64_u32 v[74:75], s[0:1], v75, s16, v[72:73]
	v_mov_b32_e32 v79, v74
	v_cmp_gt_i32_e64 s[40:41], 64, v131
	v_lshl_add_u64 v[74:75], v[78:79], 0, s[90:91]
	v_lshl_add_u64 v[68:69], v[68:69], 0, v[172:173]
	v_cndmask_b32_e64 v78, 0, v131, s[40:41]
	v_ashrrev_i32_e32 v79, 31, v78
	v_lshl_add_u64 v[78:79], s[88:89], 0, v[78:79]
	v_add_co_u32_e32 v68, vcc, s17, v68
	v_mad_u64_u32 v[84:85], s[0:1], v78, s16, v[66:67]
	s_nop 0
	v_addc_co_u32_e32 v69, vcc, 0, v69, vcc
	v_lshl_add_u64 v[70:71], v[70:71], 0, v[172:173]
	v_mov_b32_e32 v72, v85
	v_add_co_u32_e32 v70, vcc, s17, v70
	v_mad_u64_u32 v[78:79], s[0:1], v79, s16, v[72:73]
	s_nop 0
	v_addc_co_u32_e32 v71, vcc, 0, v71, vcc
	v_lshl_add_u64 v[74:75], v[74:75], 0, v[172:173]
	v_mov_b32_e32 v85, v78
	v_add_co_u32_e32 v74, vcc, s17, v74
	v_lshl_add_u64 v[78:79], v[84:85], 0, s[90:91]
	s_nop 0
	v_addc_co_u32_e32 v75, vcc, 0, v75, vcc
	v_lshl_add_u64 v[78:79], v[78:79], 0, v[172:173]
	v_ashrrev_i32_e32 v150, 3, v83
	v_add_co_u32_e32 v102, vcc, s17, v78
	v_cmp_gt_i32_e64 s[38:39], 64, v150
	s_nop 0
	v_addc_co_u32_e32 v103, vcc, 0, v79, vcc
	global_load_ushort v91, v[68:69], off
	global_load_ushort v92, v[68:69], off offset:1024
	global_load_ushort v84, v[70:71], off
	global_load_ushort v85, v[70:71], off offset:1024
	global_load_ushort v79, v[74:75], off
	global_load_ushort v80, v[74:75], off offset:1024
	global_load_ushort v77, v[102:103], off
	global_load_ushort v78, v[102:103], off offset:1024
	v_cndmask_b32_e64 v68, 0, v150, s[38:39]
	v_ashrrev_i32_e32 v69, 31, v68
	v_lshl_add_u64 v[68:69], s[88:89], 0, v[68:69]
	v_mad_u64_u32 v[66:67], s[0:1], v68, s16, v[66:67]
	v_mov_b32_e32 v68, v67
	v_mad_u64_u32 v[68:69], s[0:1], v69, s16, v[68:69]
	v_and_b32_e32 v151, 7, v83
	v_mov_b32_e32 v67, v68
	s_lshl_b32 s0, s21, 1
	s_mov_b32 s1, s91
	v_lshl_add_u64 v[66:67], v[66:67], 0, s[0:1]
	v_lshlrev_b32_e32 v68, 6, v151
	v_mov_b32_e32 v69, v173
	v_lshl_add_u64 v[66:67], v[66:67], 0, v[68:69]
	s_mov_b64 s[18:19], 0x2000
	v_lshl_add_u64 v[68:69], v[66:67], 0, s[18:19]
	v_add_co_u32_e32 v66, vcc, 0x2000, v66
	s_nop 1
	v_addc_co_u32_e32 v67, vcc, 0, v67, vcc
	global_load_dwordx4 v[114:117], v[66:67], off
	global_load_dwordx4 v[102:105], v[68:69], off offset:48
	global_load_dwordx4 v[106:109], v[68:69], off offset:32
	global_load_dwordx4 v[110:113], v[68:69], off offset:16
	v_ashrrev_i32_e32 v206, 5, v83
	v_and_b32_e32 v205, 31, v83
	v_ashrrev_i32_e32 v207, 31, v206
	v_lshl_add_u64 v[224:225], s[88:89], 0, v[206:207]
	v_mov_b64_e32 v[226:227], s[92:93]
	v_mad_u64_u32 v[226:227], s[82:83], v224, s16, v[226:227]
	v_mov_b32_e32 v224, v227
	v_mad_u64_u32 v[224:225], s[82:83], v225, s16, v[224:225]
	v_mov_b32_e32 v227, v224
	v_lshl_add_u64 v[224:225], v[226:227], 0, s[0:1]
	v_lshlrev_b32_e32 v226, 4, v205
	v_mov_b32_e32 v227, v173
	v_lshl_add_u64 v[224:225], v[224:225], 0, v[226:227]
	v_add_co_u32_e32 v224, vcc, 0x1000, v224
	s_nop 1
	v_addc_co_u32_e32 v225, vcc, 0, v225, vcc
	global_load_dwordx4 v[208:211], v[224:225], off offset:2048
	v_add_co_u32_e32 v224, vcc, 0x70000, v224
	s_nop 1
	v_addc_co_u32_e32 v225, vcc, 0, v225, vcc
	global_load_dwordx4 v[212:215], v[224:225], off offset:2048
	v_add_co_u32_e32 v224, vcc, 0x70000, v224
	s_nop 1
	v_addc_co_u32_e32 v225, vcc, 0, v225, vcc
	global_load_dwordx4 v[216:219], v[224:225], off offset:2048
	v_add_co_u32_e32 v224, vcc, 0x70000, v224
	s_nop 1
	v_addc_co_u32_e32 v225, vcc, 0, v225, vcc
	global_load_dwordx4 v[220:223], v[224:225], off offset:2048
	v_mul_u32_u24_e32 v204, 0x210, v206
	v_lshl_add_u32 v204, v205, 4, v204
	v_add_u32_e32 v204, 0xf400, v204
	v_cmp_gt_i32_e32 vcc, s4, v83
	s_and_saveexec_b64 s[18:19], vcc
	s_cbranch_execz .LBB0_783
	v_ashrrev_i32_e32 v70, 2, v83
	v_ashrrev_i32_e32 v71, 31, v70
	v_lshl_add_u64 v[66:67], s[88:89], 0, v[70:71]
	v_lshlrev_b64 v[66:67], 6, v[66:67]
	v_lshlrev_b32_e32 v68, 4, v83
	v_lshl_add_u64 v[66:67], s[36:37], 0, v[66:67]
	v_and_b32_e32 v74, 48, v68
	v_mov_b32_e32 v75, v173
	v_lshl_add_u64 v[178:179], v[66:67], 0, v[74:75]
	v_add_co_u32_e32 v166, vcc, 0x90000, v178
	global_load_dwordx4 v[66:69], v[178:179], off
	s_nop 0
	v_addc_co_u32_e32 v167, vcc, 0, v179, vcc
	global_load_dwordx4 v[166:169], v[166:167], off
	v_lshlrev_b32_e32 v70, 6, v70
	v_add3_u32 v70, s13, v70, v74
	v_add_co_u32_e32 v228, vcc, 0x120000, v178
	s_nop 1
	v_addc_co_u32_e32 v229, vcc, 0, v179, vcc
	global_load_dwordx4 v[230:233], v[228:229], off
	v_add_co_u32_e32 v228, vcc, 0x1b0000, v178
	s_nop 1
	v_addc_co_u32_e32 v229, vcc, 0, v179, vcc
	global_load_dwordx4 v[234:237], v[228:229], off
	s_waitcnt vmcnt(0)
	v_pk_add_f32 v[182:183], v[66:67], v[166:167]
	v_pk_add_f32 v[180:181], v[68:69], v[168:169]
	v_pk_add_f32 v[68:69], v[232:233], v[236:237]
	v_pk_add_f32 v[66:67], v[230:231], v[234:235]
	v_pk_add_f32 v[68:69], v[180:181], v[68:69]
	v_pk_add_f32 v[66:67], v[182:183], v[66:67]
	ds_write_b128 v70, v[66:69]
.LBB0_783:
	s_or_b64 exec, exec, s[18:19]
	v_and_b32_e32 v154, 31, v83
	s_waitcnt vmcnt(0)
	ds_write_b128 v204, v[208:211]
	ds_write_b128 v204, v[212:215] offset:8448
	ds_write_b128 v204, v[216:219] offset:16896
	ds_write_b128 v204, v[220:223] offset:25344
	v_mov_b32_e32 v66, 0
	v_mov_b32_e32 v70, 0
	s_waitcnt lgkmcnt(0)
	s_barrier
	s_and_saveexec_b64 s[18:19], s[70:71]
	s_cbranch_execz .LBB0_793
	v_lshl_add_u32 v67, v76, 10, 0
	v_add_u32_e32 v67, 0x17800, v67
	ds_read_b128 v[68:71], v67
	ds_read_b128 v[166:169], v67 offset:16
	ds_read_b128 v[178:181], v67 offset:32
	ds_read_b128 v[182:185], v67 offset:48
	s_waitcnt lgkmcnt(3)
	v_mov_b32_e32 v74, v68
	s_waitcnt lgkmcnt(2)
	v_mov_b32_e32 v75, v166
	v_mov_b32_e32 v166, v69
	v_pk_mul_f32 v[68:69], v[136:137], v[166:167]
	s_nop 0
	v_pk_fma_f32 v[68:69], v[134:135], v[74:75], v[68:69]
	v_mov_b32_e32 v74, v70
	v_mov_b32_e32 v75, v168
	v_pk_fma_f32 v[68:69], v[138:139], v[74:75], v[68:69]
	v_mov_b32_e32 v168, v71
	v_pk_fma_f32 v[68:69], v[140:141], v[168:169], v[68:69]
	s_nop 0
	v_add_f32_e32 v67, v153, v68
	v_add_f32_e32 v67, v67, v69
	s_waitcnt lgkmcnt(0)
	v_mov_b32_e32 v69, v182
	v_mov_b32_e32 v182, v179
	v_mov_b32_e32 v68, v178
	v_pk_mul_f32 v[70:71], v[144:145], v[182:183]
	s_nop 0
	v_pk_fma_f32 v[68:69], v[142:143], v[68:69], v[70:71]
	v_mov_b32_e32 v70, v180
	v_mov_b32_e32 v71, v184
	v_pk_fma_f32 v[68:69], v[146:147], v[70:71], v[68:69]
	v_mov_b32_e32 v184, v181
	v_pk_fma_f32 v[68:69], v[148:149], v[184:185], v[68:69]
	s_nop 0
	v_add_f32_e32 v67, v67, v68
	v_add_f32_e32 v67, v67, v69
	v_mul_f32_e64 v68, |v67|, s75
	v_exp_f32_e32 v68, v68
	v_min_f32_e32 v67, 0, v67
	v_add_f32_e32 v68, 1.0, v68
	v_cmp_gt_f32_e32 vcc, s25, v68
	s_nop 1
	v_cndmask_b32_e64 v69, 0, 32, vcc
	v_ldexp_f32 v68, v68, v69
	v_log_f32_e32 v68, v68
	s_nop 0
	v_mul_f32_e32 v69, 0x3f317217, v68
	v_fma_f32 v69, v68, s72, -v69
	v_fmac_f32_e32 v69, 0x3377d1cf, v68
	v_fmac_f32_e32 v69, 0x3f317217, v68
	v_cmp_lt_f32_e64 s[0:1], |v68|, s74
	s_nop 1
	v_cndmask_b32_e64 v68, v68, v69, s[0:1]
	v_cndmask_b32_e32 v69, 0, v202, vcc
	v_sub_f32_e32 v68, v68, v69
	v_sub_f32_e32 v67, v67, v68
	v_fma_f32 v70, v67, s73, 0
